# v11 + K-loop header aligned to 64 bytes (placement experiment)
# baseline (speedup 1.0000x reference)
.LBB0_343:
	s_mov_b32 s2, 0
	s_mov_b64 s[0:1], 0x100
	v_mov_b64_e32 v[18:19], v[184:185]
	v_mov_b64_e32 v[132:133], v[182:183]
	s_mov_b64 s[6:7], 0x80
	s_mov_b64 s[8:9], 0x100
	.p2align 6
